# attention unit epilogue: v_permlane32_swap pairs give each lane 16 contiguous output bytes, 4 dwordx4 stores instead of 8 dwordx2 (on top of st3)
# speedup vs baseline: 1.0130x; 1.0008x over previous
; __device__ __forceinline__ unsigned pk2(float lo, float hi) { const f32x2 v = {lo, hi}; return __builtin_bit_cast(unsigned, __builtin_convertvector(v, hwbf16x2)); }
; __device__ __forceinline__ void attn_prompt_unit(const Params& P, LAS unsigned char* lds, int li, int b, int h, int g4, const int tid) {
;     ...
;     l += __shfl_xor(l, 32);
;     const float rl = 1.0f / l;
;     bf16_t* op = MIX + qrow * DM + h * 64;
; #pragma unroll
;     for (int dh = 0; dh < 2; ++dh)
; #pragma unroll
;         for (int r4 = 0; r4 < 4; ++r4) {
;             u32x2 w; w.x = pk2(o[dh][4 * r4] * rl, o[dh][4 * r4 + 1] * rl); w.y = pk2(o[dh][4 * r4 + 2] * rl, o[dh][4 * r4 + 3] * rl);
;             *(u32x2*)(op + 32 * dh + 8 * r4 + 4 * hi) = w;
;         }
.LBB0_68:
	v_and_b32_e32 v33, 64, v200
	v_xor_b32_e32 v32, 32, v200
	s_waitcnt vmcnt(5)
	v_add_u32_e32 v67, 64, v33
	v_cmp_lt_i32_e32 vcc, v32, v67
	v_mov_b32_e32 v103, v161
	s_add_i32 s13, s13, 4
	v_cndmask_b32_e32 v32, v200, v32, vcc
	v_lshlrev_b32_e32 v66, 2, v32
	ds_bpermute_b32 v34, v66, v101
	v_lshlrev_b64 v[32:33], 11, v[104:105]
	s_add_i32 s14, s14, 4
	s_add_i32 s12, s12, 4
	s_waitcnt lgkmcnt(0)
	v_add_f32_e32 v34, v101, v34
	v_div_scale_f32 v35, s[0:1], v34, v34, 1.0
	v_rcp_f32_e32 v36, v35
	v_div_scale_f32 v37, vcc, 1.0, v34, 1.0
	v_readlane_b32 s0, v247, 5
	v_fma_f32 v38, -v35, v36, 1.0
	v_fmac_f32_e32 v36, v38, v36
	v_mul_f32_e32 v38, v37, v36
	v_fma_f32 v39, -v35, v38, v37
	v_fmac_f32_e32 v38, v39, v36
	v_fma_f32 v35, -v35, v38, v37
	v_readlane_b32 s1, v247, 6
	v_div_fmas_f32 v35, v35, v36, v38
	v_div_fixup_f32 v34, v35, v34, 1.0
	v_lshl_add_u64 v[32:33], s[0:1], 0, v[32:33]
	v_lshl_add_u64 v[32:33], v[32:33], 0, s[36:37]
	v_pk_mul_f32 v[0:1], v[0:1], v[34:35] op_sel_hi:[1,0]
	v_pk_mul_f32 v[2:3], v[2:3], v[34:35] op_sel_hi:[1,0]
	v_pk_mul_f32 v[4:5], v[4:5], v[34:35] op_sel_hi:[1,0]
	v_pk_mul_f32 v[6:7], v[6:7], v[34:35] op_sel_hi:[1,0]
	v_pk_mul_f32 v[8:9], v[8:9], v[34:35] op_sel_hi:[1,0]
	v_pk_mul_f32 v[10:11], v[10:11], v[34:35] op_sel_hi:[1,0]
	v_pk_mul_f32 v[12:13], v[12:13], v[34:35] op_sel_hi:[1,0]
	v_pk_mul_f32 v[14:15], v[14:15], v[34:35] op_sel_hi:[1,0]
	v_pk_mul_f32 v[16:17], v[16:17], v[34:35] op_sel_hi:[1,0]
	v_pk_mul_f32 v[18:19], v[18:19], v[34:35] op_sel_hi:[1,0]
	v_pk_mul_f32 v[20:21], v[20:21], v[34:35] op_sel_hi:[1,0]
	v_pk_mul_f32 v[22:23], v[22:23], v[34:35] op_sel_hi:[1,0]
	v_pk_mul_f32 v[24:25], v[24:25], v[34:35] op_sel_hi:[1,0]
	v_pk_mul_f32 v[26:27], v[26:27], v[34:35] op_sel_hi:[1,0]
	v_pk_mul_f32 v[28:29], v[28:29], v[34:35] op_sel_hi:[1,0]
	v_pk_mul_f32 v[30:31], v[30:31], v[34:35] op_sel_hi:[1,0]
	v_lshl_add_u64 v[32:33], v[32:33], 0, v[102:103]
	v_lshl_add_u64 v[32:33], v[32:33], 0, v[102:103]
	v_cvt_pk_bf16_f32 v16, v16, v17
	v_cvt_pk_bf16_f32 v17, v18, v19
	v_cvt_pk_bf16_f32 v18, v20, v21
	v_cvt_pk_bf16_f32 v19, v22, v23
	v_cvt_pk_bf16_f32 v20, v24, v25
	v_cvt_pk_bf16_f32 v21, v26, v27
	v_cvt_pk_bf16_f32 v22, v28, v29
	v_cvt_pk_bf16_f32 v23, v30, v31
	v_cvt_pk_bf16_f32 v0, v0, v1
	v_cvt_pk_bf16_f32 v1, v2, v3
	v_cvt_pk_bf16_f32 v2, v4, v5
	v_cvt_pk_bf16_f32 v3, v6, v7
	v_cvt_pk_bf16_f32 v4, v8, v9
	v_cvt_pk_bf16_f32 v5, v10, v11
	v_cvt_pk_bf16_f32 v6, v12, v13
	v_cvt_pk_bf16_f32 v7, v14, v15
	v_permlane32_swap_b32_e32 v16, v18
	v_permlane32_swap_b32_e32 v17, v19
	v_permlane32_swap_b32_e32 v20, v22
	v_permlane32_swap_b32_e32 v21, v23
	v_permlane32_swap_b32_e32 v0, v2
	v_permlane32_swap_b32_e32 v1, v3
	v_permlane32_swap_b32_e32 v4, v6
	v_permlane32_swap_b32_e32 v5, v7
	global_store_dwordx4 v[32:33], v[16:19], off
	global_store_dwordx4 v[32:33], v[20:23], off offset:32
	global_store_dwordx4 v[32:33], v[0:3], off offset:64
	global_store_dwordx4 v[32:33], v[4:7], off offset:96
	s_add_i32 s0, s2, 1
	s_cmp_eq_u32 s2, s4
	s_mov_b32 s2, s0
	s_nop 1
	s_cbranch_scc1 .LBB0_87

; #define LDS_BARRIER() asm volatile("s_waitcnt lgkmcnt(0)\n\ts_barrier" ::: "memory")
; #define AT_LOAD(K_, V_, kt) do { const bf16_t* s_ = kvsrc + (size_t)(kt) * 64 * NQKV; K_ = *(const bf16x8*)s_; V_ = *(const bf16x8*)(s_ + 1024); } while (0)
; #define AT_STORE(K_, V_, buf) do { *(LAS bf16x8*)(lds + AT_KOFF + (buf) * 9216 + srow * 144 + sch * 16) = K_; \
;         _Pragma("unroll") for (int j_ = 0; j_ < 8; ++j_) *(LAS short*)(lds + AT_VOFF + (buf) * 9216 + (8 * sch + j_) * 144 + vp * 2) = V_[j_]; } while (0)
; __device__ __forceinline__ void attn_prompt_unit(const Params& P, LAS unsigned char* lds, int li, int b, int h, int g4, const int tid) {
;     ...
;     for (int kt = kt_lo; kt <= kt_hi; kt += 2) {
;         if (kt + 2 <= kt_hi) AT_LOAD(kA, vA, kt + 2);
;         if (kt >= cw - 8 && kt <= cw) attn_tile(lds + AT_KOFF, lds + AT_VOFF, btl + min(cw - kt, 3) * 1024, qr, o, m, l, r32, hi);
;         AT_STORE(kB, vB, 1);
;         LDS_BARRIER();
;         if (kt + 3 <= kt_hi) AT_LOAD(kB, vB, kt + 3);
;         if (kt + 1 >= cw - 8 && kt + 1 <= cw) attn_tile(lds + AT_KOFF + 9216, lds + AT_VOFF + 9216, btl + min(cw - kt - 1, 3) * 1024, qr, o, m, l, r32, hi);
;         if (kt + 2 <= kt_hi) AT_STORE(kA, vA, 0);
;         LDS_BARRIER();
;     }
.LBB0_85:
	s_waitcnt lgkmcnt(0)
	s_barrier
	s_andn2_b64 vcc, exec, s[0:1]
	s_mov_b64 s[0:1], 0xc0000
	s_add_i32 s26, s26, -2
	v_lshl_add_u64 v[106:107], v[106:107], 0, s[0:1]
	s_cbranch_vccz .LBB0_68
	s_mov_b32 s28, s27
	s_branch .LBB0_71
	s_nop 0
	s_nop 0
	s_nop 0
	s_nop 0
	s_nop 0
	s_nop 0
	s_nop 0
	s_nop 0
	s_nop 0
	s_nop 0
	s_nop 0
	s_nop 0
	s_nop 0
